# full stack + P9: 32-bit saddr expert-row addressing (no 64-bit mads) and v-accumulate as fma chains (64 instead of 96 packed ops per batch)
# speedup vs baseline: 1.0159x; 1.0093x over previous
.LpA_kb:
	s_waitcnt vmcnt(0)
	s_cmp_lt_u32 s34, 8
	s_cselect_b64 s[2:3], -1, 0
	s_nop 0
	v_cndmask_b32_e64 v5, v212, v211, s[2:3]
	s_add_i32 s60, s33, 0
	v_readlane_b32 s16, v5, s60
	s_add_i32 s61, s33, 1
	v_readlane_b32 s18, v5, s61
	s_add_i32 s62, s33, 2
	v_readlane_b32 s35, v5, s62
	s_add_i32 s63, s33, 3
	v_readlane_b32 s36, v5, s63
	s_add_i32 s60, s33, 4
	v_readlane_b32 s20, v5, s60
	s_add_i32 s61, s33, 5
	v_readlane_b32 s22, v5, s61
	s_add_i32 s62, s33, 6
	v_readlane_b32 s24, v5, s62
	s_add_i32 s63, s33, 7
	v_readlane_b32 s26, v5, s63
	v_mad_u32_u24 v6, s18, v202, v138
	global_load_dwordx3 v[2:4], v6, s[78:79]
	v_mad_u32_u24 v8, s16, v202, v138
	global_load_dwordx3 v[48:50], v8, s[78:79]
	v_mad_u32_u24 v10, s36, v202, v138
	global_load_dwordx3 v[80:82], v10, s[78:79]
	v_mad_u32_u24 v12, s35, v202, v138
	global_load_dwordx3 v[54:56], v12, s[78:79]
	v_mad_u32_u24 v6, s22, v202, v138
	global_load_dwordx3 v[84:86], v6, s[78:79]
	v_mad_u32_u24 v8, s20, v202, v138
	global_load_dwordx3 v[60:62], v8, s[78:79]
	v_mad_u32_u24 v10, s24, v202, v138
	global_load_dwordx3 v[76:78], v10, s[78:79]
	v_mad_u32_u24 v12, s26, v202, v138
	global_load_dwordx3 v[88:90], v12, s[78:79]
	s_add_i32 s60, s33, 8
	v_readlane_b32 s16, v5, s60
	s_add_i32 s61, s33, 9
	v_readlane_b32 s18, v5, s61
	s_add_i32 s62, s33, 10
	v_readlane_b32 s35, v5, s62
	s_add_i32 s63, s33, 11
	v_readlane_b32 s36, v5, s63
	s_add_i32 s60, s33, 12
	v_readlane_b32 s20, v5, s60
	s_add_i32 s61, s33, 13
	v_readlane_b32 s22, v5, s61
	s_add_i32 s62, s33, 14
	v_readlane_b32 s24, v5, s62
	s_add_i32 s63, s33, 15
	v_readlane_b32 s26, v5, s63
	v_mad_u32_u24 v6, s16, v202, v138
	global_load_dwordx3 v[34:36], v6, s[78:79]
	v_mad_u32_u24 v8, s18, v202, v138
	global_load_dwordx3 v[44:46], v8, s[78:79]
	v_mad_u32_u24 v10, s35, v202, v138
	global_load_dwordx3 v[66:68], v10, s[78:79]
	v_mad_u32_u24 v12, s36, v202, v138
	global_load_dwordx3 v[40:42], v12, s[78:79]
	v_mad_u32_u24 v6, s20, v202, v138
	global_load_dwordx3 v[98:100], v6, s[78:79]
	v_mad_u32_u24 v8, s22, v202, v138
	global_load_dwordx3 v[72:74], v8, s[78:79]
	v_mad_u32_u24 v10, s24, v202, v138
	global_load_dwordx3 v[130:132], v10, s[78:79]
	v_mad_u32_u24 v12, s26, v202, v138
	global_load_dwordx3 v[104:106], v12, s[78:79]
	s_waitcnt vmcnt(8)

.LpB_kb:
	s_waitcnt vmcnt(0)
	s_cmp_lt_u32 s34, 8
	s_cselect_b64 s[2:3], -1, 0
	s_nop 0
	v_cndmask_b32_e64 v5, v212, v211, s[2:3]
	s_add_i32 s60, s33, 0
	v_readlane_b32 s16, v5, s60
	s_add_i32 s61, s33, 1
	v_readlane_b32 s18, v5, s61
	s_add_i32 s62, s33, 2
	v_readlane_b32 s35, v5, s62
	s_add_i32 s63, s33, 3
	v_readlane_b32 s36, v5, s63
	s_add_i32 s60, s33, 4
	v_readlane_b32 s20, v5, s60
	s_add_i32 s61, s33, 5
	v_readlane_b32 s22, v5, s61
	s_add_i32 s62, s33, 6
	v_readlane_b32 s24, v5, s62
	s_add_i32 s63, s33, 7
	v_readlane_b32 s26, v5, s63
	v_mad_u32_u24 v6, s16, v202, v138
	global_load_dwordx3 v[34:36], v6, s[80:81]
	v_mad_u32_u24 v8, s18, v202, v138
	global_load_dwordx3 v[44:46], v8, s[80:81]
	v_mad_u32_u24 v10, s35, v202, v138
	global_load_dwordx3 v[66:68], v10, s[80:81]
	v_mad_u32_u24 v12, s36, v202, v138
	global_load_dwordx3 v[40:42], v12, s[80:81]
	v_mad_u32_u24 v6, s20, v202, v138
	global_load_dwordx3 v[98:100], v6, s[80:81]
	v_mad_u32_u24 v8, s22, v202, v138
	global_load_dwordx3 v[72:74], v8, s[80:81]
	v_mad_u32_u24 v10, s24, v202, v138
	global_load_dwordx3 v[130:132], v10, s[80:81]
	v_mad_u32_u24 v12, s26, v202, v138
	global_load_dwordx3 v[104:106], v12, s[80:81]
	s_add_i32 s60, s33, 8
	v_readlane_b32 s16, v5, s60
	s_add_i32 s61, s33, 9
	v_readlane_b32 s18, v5, s61
	s_add_i32 s62, s33, 10
	v_readlane_b32 s35, v5, s62
	s_add_i32 s63, s33, 11
	v_readlane_b32 s36, v5, s63
	s_add_i32 s60, s33, 12
	v_readlane_b32 s20, v5, s60
	s_add_i32 s61, s33, 13
	v_readlane_b32 s22, v5, s61
	s_add_i32 s62, s33, 14
	v_readlane_b32 s24, v5, s62
	s_add_i32 s63, s33, 15
	v_readlane_b32 s26, v5, s63
	v_mad_u32_u24 v6, s16, v202, v138
	global_load_dwordx3 v[216:218], v6, s[80:81]
	v_mad_u32_u24 v8, s18, v202, v138
	global_load_dwordx3 v[220:222], v8, s[80:81]
	v_mad_u32_u24 v10, s35, v202, v138
	global_load_dwordx3 v[224:226], v10, s[80:81]
	v_mad_u32_u24 v12, s36, v202, v138
	global_load_dwordx3 v[228:230], v12, s[80:81]
	v_mad_u32_u24 v6, s20, v202, v138
	global_load_dwordx3 v[232:234], v6, s[80:81]
	v_mad_u32_u24 v8, s22, v202, v138
	global_load_dwordx3 v[236:238], v8, s[80:81]
	v_mad_u32_u24 v10, s24, v202, v138
	global_load_dwordx3 v[240:242], v10, s[80:81]
	v_mad_u32_u24 v12, s26, v202, v138
	global_load_dwordx3 v[244:246], v12, s[80:81]
	s_waitcnt vmcnt(8)
.LpB_half:
	s_cmp_lt_u32 s34, 8
	s_cselect_b64 s[2:3], -1, 0
	v_and_or_b32 v5, s33, 56, v231
	v_lshlrev_b32_e32 v5, 2, v5
	v_cndmask_b32_e64 v2, v214, v213, s[2:3]
	s_nop 0
	ds_bpermute_b32 v107, v5, v2
	s_waitcnt lgkmcnt(0)
	s_nop 0
	v_mov_b32_e32 v37, v44
	v_mov_b32_e32 v38, v45
	v_mov_b32_e32 v39, v46
	v_mov_b32_e32 v69, v40
	v_mov_b32_e32 v70, v41
	v_mov_b32_e32 v71, v42
	v_mov_b32_e32 v101, v72
	v_mov_b32_e32 v102, v73
	v_mov_b32_e32 v103, v74
	v_mov_b32_e32 v133, v104
	v_mov_b32_e32 v134, v105
	v_mov_b32_e32 v135, v106
	v_readlane_b32 s2, v107, 0
	v_readlane_b32 s14, v107, 1
	v_readlane_b32 s16, v107, 2
	v_readlane_b32 s18, v107, 3
	v_readlane_b32 s20, v107, 4
	v_readlane_b32 s22, v107, 5
	v_readlane_b32 s24, v107, 6
	v_readlane_b32 s26, v107, 7
	v_cvt_scalef32_pk32_f32_fp6 v[2:33], v[34:39], 1.0
	v_cvt_scalef32_pk32_f32_fp6 v[34:65], v[66:71], 1.0
	v_cvt_scalef32_pk32_f32_fp6 v[66:97], v[98:103], 1.0
	v_cvt_scalef32_pk32_f32_fp6 v[98:129], v[130:135], 1.0
	v_pk_fma_f32 v[178:179], v[2:3], s[2:3], v[178:179] op_sel_hi:[1,0,1]
	v_pk_fma_f32 v[176:177], v[4:5], s[2:3], v[176:177] op_sel_hi:[1,0,1]
	v_pk_fma_f32 v[174:175], v[6:7], s[2:3], v[174:175] op_sel_hi:[1,0,1]
	v_pk_fma_f32 v[172:173], v[8:9], s[2:3], v[172:173] op_sel_hi:[1,0,1]
	v_pk_fma_f32 v[170:171], v[10:11], s[2:3], v[170:171] op_sel_hi:[1,0,1]
	v_pk_fma_f32 v[168:169], v[12:13], s[2:3], v[168:169] op_sel_hi:[1,0,1]
	v_pk_fma_f32 v[166:167], v[14:15], s[2:3], v[166:167] op_sel_hi:[1,0,1]
	v_pk_fma_f32 v[180:181], v[16:17], s[2:3], v[180:181] op_sel_hi:[1,0,1]
	v_pk_fma_f32 v[178:179], v[18:19], s[14:15], v[178:179] op_sel_hi:[1,0,1]
	v_pk_fma_f32 v[176:177], v[20:21], s[14:15], v[176:177] op_sel_hi:[1,0,1]
	v_pk_fma_f32 v[174:175], v[22:23], s[14:15], v[174:175] op_sel_hi:[1,0,1]
	v_pk_fma_f32 v[172:173], v[24:25], s[14:15], v[172:173] op_sel_hi:[1,0,1]
	v_pk_fma_f32 v[170:171], v[26:27], s[14:15], v[170:171] op_sel_hi:[1,0,1]
	v_pk_fma_f32 v[168:169], v[28:29], s[14:15], v[168:169] op_sel_hi:[1,0,1]
	v_pk_fma_f32 v[166:167], v[30:31], s[14:15], v[166:167] op_sel_hi:[1,0,1]
	v_pk_fma_f32 v[180:181], v[32:33], s[14:15], v[180:181] op_sel_hi:[1,0,1]
	v_pk_fma_f32 v[178:179], v[34:35], s[16:17], v[178:179] op_sel_hi:[1,0,1]
	v_pk_fma_f32 v[176:177], v[36:37], s[16:17], v[176:177] op_sel_hi:[1,0,1]
	v_pk_fma_f32 v[174:175], v[38:39], s[16:17], v[174:175] op_sel_hi:[1,0,1]
	v_pk_fma_f32 v[172:173], v[40:41], s[16:17], v[172:173] op_sel_hi:[1,0,1]
	v_pk_fma_f32 v[170:171], v[42:43], s[16:17], v[170:171] op_sel_hi:[1,0,1]
	v_pk_fma_f32 v[168:169], v[44:45], s[16:17], v[168:169] op_sel_hi:[1,0,1]
	v_pk_fma_f32 v[166:167], v[46:47], s[16:17], v[166:167] op_sel_hi:[1,0,1]
	v_pk_fma_f32 v[180:181], v[48:49], s[16:17], v[180:181] op_sel_hi:[1,0,1]
	v_pk_fma_f32 v[178:179], v[50:51], s[18:19], v[178:179] op_sel_hi:[1,0,1]
	v_pk_fma_f32 v[176:177], v[52:53], s[18:19], v[176:177] op_sel_hi:[1,0,1]
	v_pk_fma_f32 v[174:175], v[54:55], s[18:19], v[174:175] op_sel_hi:[1,0,1]
	v_pk_fma_f32 v[172:173], v[56:57], s[18:19], v[172:173] op_sel_hi:[1,0,1]
	v_pk_fma_f32 v[170:171], v[58:59], s[18:19], v[170:171] op_sel_hi:[1,0,1]
	v_pk_fma_f32 v[168:169], v[60:61], s[18:19], v[168:169] op_sel_hi:[1,0,1]
	v_pk_fma_f32 v[166:167], v[62:63], s[18:19], v[166:167] op_sel_hi:[1,0,1]
	v_pk_fma_f32 v[180:181], v[64:65], s[18:19], v[180:181] op_sel_hi:[1,0,1]
	v_pk_fma_f32 v[178:179], v[66:67], s[20:21], v[178:179] op_sel_hi:[1,0,1]
	v_pk_fma_f32 v[176:177], v[68:69], s[20:21], v[176:177] op_sel_hi:[1,0,1]
	v_pk_fma_f32 v[174:175], v[70:71], s[20:21], v[174:175] op_sel_hi:[1,0,1]
	v_pk_fma_f32 v[172:173], v[72:73], s[20:21], v[172:173] op_sel_hi:[1,0,1]
	v_pk_fma_f32 v[170:171], v[74:75], s[20:21], v[170:171] op_sel_hi:[1,0,1]
	v_pk_fma_f32 v[168:169], v[76:77], s[20:21], v[168:169] op_sel_hi:[1,0,1]
	v_pk_fma_f32 v[166:167], v[78:79], s[20:21], v[166:167] op_sel_hi:[1,0,1]
	v_pk_fma_f32 v[180:181], v[80:81], s[20:21], v[180:181] op_sel_hi:[1,0,1]
	v_pk_fma_f32 v[178:179], v[82:83], s[22:23], v[178:179] op_sel_hi:[1,0,1]
	v_pk_fma_f32 v[176:177], v[84:85], s[22:23], v[176:177] op_sel_hi:[1,0,1]
	v_pk_fma_f32 v[174:175], v[86:87], s[22:23], v[174:175] op_sel_hi:[1,0,1]
	v_pk_fma_f32 v[172:173], v[88:89], s[22:23], v[172:173] op_sel_hi:[1,0,1]
	v_pk_fma_f32 v[170:171], v[90:91], s[22:23], v[170:171] op_sel_hi:[1,0,1]
	v_pk_fma_f32 v[168:169], v[92:93], s[22:23], v[168:169] op_sel_hi:[1,0,1]
	v_pk_fma_f32 v[166:167], v[94:95], s[22:23], v[166:167] op_sel_hi:[1,0,1]
	v_pk_fma_f32 v[180:181], v[96:97], s[22:23], v[180:181] op_sel_hi:[1,0,1]
	v_pk_fma_f32 v[178:179], v[98:99], s[24:25], v[178:179] op_sel_hi:[1,0,1]
	v_pk_fma_f32 v[176:177], v[100:101], s[24:25], v[176:177] op_sel_hi:[1,0,1]
	v_pk_fma_f32 v[174:175], v[102:103], s[24:25], v[174:175] op_sel_hi:[1,0,1]
	v_pk_fma_f32 v[172:173], v[104:105], s[24:25], v[172:173] op_sel_hi:[1,0,1]
	v_pk_fma_f32 v[170:171], v[106:107], s[24:25], v[170:171] op_sel_hi:[1,0,1]
	v_pk_fma_f32 v[168:169], v[108:109], s[24:25], v[168:169] op_sel_hi:[1,0,1]
	v_pk_fma_f32 v[166:167], v[110:111], s[24:25], v[166:167] op_sel_hi:[1,0,1]
	v_pk_fma_f32 v[180:181], v[112:113], s[24:25], v[180:181] op_sel_hi:[1,0,1]
	v_pk_fma_f32 v[178:179], v[114:115], s[26:27], v[178:179] op_sel_hi:[1,0,1]
	v_pk_fma_f32 v[176:177], v[116:117], s[26:27], v[176:177] op_sel_hi:[1,0,1]
	v_pk_fma_f32 v[174:175], v[118:119], s[26:27], v[174:175] op_sel_hi:[1,0,1]
	v_pk_fma_f32 v[172:173], v[120:121], s[26:27], v[172:173] op_sel_hi:[1,0,1]
	v_pk_fma_f32 v[170:171], v[122:123], s[26:27], v[170:171] op_sel_hi:[1,0,1]
	v_pk_fma_f32 v[168:169], v[124:125], s[26:27], v[168:169] op_sel_hi:[1,0,1]
	v_pk_fma_f32 v[166:167], v[126:127], s[26:27], v[166:167] op_sel_hi:[1,0,1]
	v_pk_fma_f32 v[180:181], v[128:129], s[26:27], v[180:181] op_sel_hi:[1,0,1]
	s_add_i32 s34, s34, 1
	s_add_i32 s33, s33, 8
	s_bitcmp1_b32 s34, 0
	s_cbranch_scc0 .LpB_pair_done
	s_waitcnt vmcnt(0)
	v_mov_b32_e32 v34, v216
	v_mov_b32_e32 v35, v217
	v_mov_b32_e32 v36, v218
	v_mov_b32_e32 v44, v220
	v_mov_b32_e32 v45, v221
	v_mov_b32_e32 v46, v222
	v_mov_b32_e32 v66, v224
	v_mov_b32_e32 v67, v225
	v_mov_b32_e32 v68, v226
	v_mov_b32_e32 v40, v228
	v_mov_b32_e32 v41, v229
	v_mov_b32_e32 v42, v230
	v_mov_b32_e32 v98, v232
	v_mov_b32_e32 v99, v233
	v_mov_b32_e32 v100, v234
	v_mov_b32_e32 v72, v236
	v_mov_b32_e32 v73, v237
	v_mov_b32_e32 v74, v238
	v_mov_b32_e32 v130, v240
	v_mov_b32_e32 v131, v241
	v_mov_b32_e32 v132, v242
	v_mov_b32_e32 v104, v244
	v_mov_b32_e32 v105, v245
	v_mov_b32_e32 v106, v246
	s_branch .LpB_half
